# GQA and MLA packed exponent arguments plus row-sum chains starting from the first pair
# baseline (speedup 1.0000x reference)
.LBB0_592:
	s_cmp_lt_u32 s14, s7
	s_cselect_b32 s4, 0, s7
	s_cselect_b32 s5, s24, s1
	s_lshl_b32 s4, s4, 5
	s_sub_i32 s4, s5, s4
	s_add_i32 s30, s15, s4
	s_add_i32 s4, s10, s14
	v_add_u32_e32 v66, s30, v158
	s_cmp_lt_u32 s4, s7
	v_ashrrev_i32_e32 v67, 31, v66
	s_cselect_b32 s4, 0, s7
	v_lshlrev_b64 v[66:67], 9, v[66:67]
	s_cselect_b32 s5, s24, s1
	s_lshl_b32 s4, s4, 5
	v_add_u32_e32 v166, 0x8800, v161
	v_add_u32_e32 v167, 0xac00, v161
	v_add_u32_e32 v168, 0xd000, v161
	v_add_u32_e32 v169, 0xf400, v161
	v_lshl_add_u64 v[66:67], v[150:151], 0, v[66:67]
	s_sub_i32 s4, s5, s4
	s_add_i32 s5, s20, s15
	s_waitcnt vmcnt(7)
	ds_write_b128 v160, v[118:121]
	s_waitcnt vmcnt(6)
	ds_write2_b64 v166, v[114:115], v[116:117] offset1:1
	s_waitcnt vmcnt(5)
	ds_write_b128 v160, v[126:129] offset:8704
	s_waitcnt vmcnt(4)
	ds_write2_b64 v167, v[122:123], v[124:125] offset1:1
	s_waitcnt vmcnt(3)
	ds_write_b128 v160, v[134:137] offset:17408
	s_waitcnt vmcnt(2)
	ds_write2_b64 v168, v[130:131], v[132:133] offset1:1
	s_waitcnt vmcnt(1)
	ds_write_b128 v160, v[142:145] offset:26112
	s_waitcnt vmcnt(0)
	ds_write2_b64 v169, v[138:139], v[140:141] offset1:1
	s_waitcnt lgkmcnt(0)
	s_barrier
	global_load_dwordx4 v[118:121], v[66:67], off
	v_lshl_add_u64 v[66:67], s[30:31], 1, v[152:153]
	s_add_i32 s30, s5, s4
	s_add_i32 s4, s4, s15
	global_load_dwordx4 v[114:117], v[66:67], off
	v_add_u32_e32 v66, s4, v164
	s_add_i32 s4, s11, s14
	s_cmp_lt_u32 s4, s7
	v_ashrrev_i32_e32 v67, 31, v66
	s_cselect_b32 s4, 0, s7
	v_lshlrev_b64 v[66:67], 9, v[66:67]
	s_cselect_b32 s5, s24, s1
	s_lshl_b32 s4, s4, 5
	v_lshl_add_u64 v[66:67], v[150:151], 0, v[66:67]
	s_sub_i32 s4, s5, s4
	s_add_i32 s5, s21, s15
	global_load_dwordx4 v[126:129], v[66:67], off
	v_lshl_add_u64 v[66:67], s[30:31], 1, v[152:153]
	s_add_i32 s30, s5, s4
	s_add_i32 s4, s4, s15
	global_load_dwordx4 v[122:125], v[66:67], off
	v_add_u32_e32 v66, s4, v162
	s_add_i32 s4, s18, s14
	s_cmp_lt_u32 s4, s7
	v_ashrrev_i32_e32 v67, 31, v66
	s_cselect_b32 s4, 0, s7
	v_lshlrev_b64 v[66:67], 9, v[66:67]
	s_cselect_b32 s5, s24, s1
	s_lshl_b32 s4, s4, 5
	v_lshl_add_u64 v[66:67], v[150:151], 0, v[66:67]
	s_sub_i32 s4, s5, s4
	s_add_i32 s5, s19, s15
	global_load_dwordx4 v[134:137], v[66:67], off
	v_lshl_add_u64 v[66:67], s[30:31], 1, v[152:153]
	s_add_i32 s30, s5, s4
	s_add_i32 s4, s4, s15
	global_load_dwordx4 v[130:133], v[66:67], off
	v_add_u32_e32 v66, s4, v163
	v_ashrrev_i32_e32 v67, 31, v66
	v_lshlrev_b64 v[66:67], 9, v[66:67]
	v_lshl_add_u64 v[66:67], v[150:151], 0, v[66:67]
	global_load_dwordx4 v[142:145], v[66:67], off
	v_lshl_add_u64 v[66:67], s[30:31], 1, v[152:153]
	global_load_dwordx4 v[138:141], v[66:67], off
	ds_read_b128 v[66:69], v159
	ds_read_b128 v[176:179], v159 offset:32
	s_waitcnt lgkmcnt(1)
	v_mfma_f32_32x32x16_bf16 v[66:81], v[66:69], v[110:113], 0
	v_mov_b32_e32 v0, v149
	v_mov_b32_e32 v175, v148
	s_add_i32 s15, s15, 32
	s_add_i32 s14, s14, 1
	s_cmp_lg_u32 s20, s15
	s_waitcnt lgkmcnt(0)
	v_mfma_f32_32x32x16_bf16 v[66:81], v[176:179], v[106:109], v[66:81]
	ds_read_b128 v[176:179], v159 offset:64
	s_waitcnt lgkmcnt(0)
	v_mfma_f32_32x32x16_bf16 v[66:81], v[176:179], v[102:105], v[66:81]
	ds_read_b128 v[176:179], v159 offset:96
	s_waitcnt lgkmcnt(0)
	v_mfma_f32_32x32x16_bf16 v[66:81], v[176:179], v[98:101], v[66:81]
	ds_read_b128 v[176:179], v159 offset:128
	s_waitcnt lgkmcnt(0)
	v_mfma_f32_32x32x16_bf16 v[66:81], v[176:179], v[94:97], v[66:81]
	ds_read_b128 v[176:179], v159 offset:160
	s_waitcnt lgkmcnt(0)
	v_mfma_f32_32x32x16_bf16 v[66:81], v[176:179], v[90:93], v[66:81]
	ds_read_b128 v[176:179], v159 offset:192
	s_waitcnt lgkmcnt(0)
	v_mfma_f32_32x32x16_bf16 v[66:81], v[176:179], v[86:89], v[66:81]
	ds_read_b128 v[176:179], v159 offset:224
	s_waitcnt lgkmcnt(0)
	v_mfma_f32_32x32x16_bf16 v[66:81], v[176:179], v[82:85], v[66:81]
	s_nop 11
	v_max_f32_e32 v148, v67, v67
	v_max_f32_e32 v149, v66, v66
	v_max_f32_e32 v148, v149, v148
	v_max3_f32 v148, v148, v68, v69
	v_max3_f32 v148, v148, v70, v71
	v_max3_f32 v148, v148, v72, v73
	v_max3_f32 v148, v148, v74, v75
	v_max3_f32 v148, v148, v76, v77
	v_max3_f32 v148, v148, v78, v79
	v_max3_f32 v148, v148, v80, v81
	v_mov_b32_e32 v149, v148
	s_nop 1
	v_permlane32_swap_b32 v149, v148
	s_waitcnt lgkmcnt(0)
	v_max3_f32 v149, v0, v148, v149
	v_mov_b32_e32 v148, v81
	v_pk_mul_f32 v[176:177], v[148:149], s[28:29] op_sel_hi:[1,0]
	v_sub_f32_e32 v0, v0, v149
	v_pk_fma_f32 v[70:71], v[70:71], s[28:29], v[176:177] op_sel:[0,0,1] op_sel_hi:[1,0,1] neg_lo:[0,0,1] neg_hi:[0,0,1]
	v_pk_fma_f32 v[72:73], v[72:73], s[28:29], v[176:177] op_sel:[0,0,1] op_sel_hi:[1,0,1] neg_lo:[0,0,1] neg_hi:[0,0,1]
	v_exp_f32_e32 v81, v70
	v_exp_f32_e32 v178, v71
	v_pk_fma_f32 v[74:75], v[74:75], s[28:29], v[176:177] op_sel:[0,0,1] op_sel_hi:[1,0,1] neg_lo:[0,0,1] neg_hi:[0,0,1]
	v_exp_f32_e32 v179, v72
	v_exp_f32_e32 v73, v73
	v_pk_fma_f32 v[76:77], v[76:77], s[28:29], v[176:177] op_sel:[0,0,1] op_sel_hi:[1,0,1] neg_lo:[0,0,1] neg_hi:[0,0,1]
	v_exp_f32_e32 v74, v74
	v_exp_f32_e32 v75, v75
	v_pk_fma_f32 v[66:67], v[66:67], s[28:29], v[176:177] op_sel:[0,0,1] op_sel_hi:[1,0,1] neg_lo:[0,0,1] neg_hi:[0,0,1]
	v_exp_f32_e32 v76, v76
	v_exp_f32_e32 v77, v77
	v_pk_fma_f32 v[68:69], v[68:69], s[28:29], v[176:177] op_sel:[0,0,1] op_sel_hi:[1,0,1] neg_lo:[0,0,1] neg_hi:[0,0,1]
	v_exp_f32_e32 v66, v66
	v_exp_f32_e32 v67, v67
	v_pk_fma_f32 v[78:79], v[78:79], s[28:29], v[176:177] op_sel:[0,0,1] op_sel_hi:[1,0,1] neg_lo:[0,0,1] neg_hi:[0,0,1]
	v_exp_f32_e32 v68, v68
	v_exp_f32_e32 v69, v69
	v_fma_f32 v80, v80, s28, -v177
	v_exp_f32_e32 v78, v78
	v_exp_f32_e32 v79, v79
	v_exp_f32_e32 v80, v80
	v_sub_f32_e32 v70, v176, v177
	v_exp_f32_e32 v176, v70
	v_add_f32_e32 v70, v67, v66
	v_add_f32_e32 v70, v68, v70
	v_add_f32_e32 v70, v69, v70
	v_add_f32_e32 v70, v81, v70
	v_add_f32_e32 v70, v178, v70
	v_add_f32_e32 v70, v179, v70
	v_add_f32_e32 v70, v73, v70
	v_add_f32_e32 v70, v74, v70
	v_add_f32_e32 v70, v75, v70
	v_add_f32_e32 v70, v76, v70
	v_add_f32_e32 v70, v77, v70
	v_add_f32_e32 v70, v78, v70
	v_mul_f32_e32 v0, 0x3e0293ee, v0
	v_add_f32_e32 v70, v79, v70
	v_exp_f32_e32 v0, v0
	v_add_f32_e32 v70, v80, v70
	v_cvt_pk_bf16_f32 v73, v179, v73
	v_add_u32_e32 v179, 0x8800, v165
	v_add_f32_e32 v148, v176, v70
	v_cvt_pk_bf16_f32 v70, v66, v67
	v_cvt_pk_bf16_f32 v71, v68, v69
	v_cvt_pk_bf16_f32 v72, v81, v178
	v_cvt_pk_bf16_f32 v66, v74, v75
	v_cvt_pk_bf16_f32 v67, v76, v77
	v_cvt_pk_bf16_f32 v68, v78, v79
	v_cvt_pk_bf16_f32 v69, v80, v176
	ds_read2_b64 v[74:77], v179 offset1:2
	ds_read2_b64 v[78:81], v179 offset0:4 offset1:6
	v_pk_mul_f32 v[64:65], v[64:65], v[0:1] op_sel_hi:[1,0]
	v_pk_mul_f32 v[62:63], v[62:63], v[0:1] op_sel_hi:[1,0]
	v_pk_mul_f32 v[60:61], v[60:61], v[0:1] op_sel_hi:[1,0]
	v_pk_mul_f32 v[58:59], v[58:59], v[0:1] op_sel_hi:[1,0]
	v_pk_mul_f32 v[56:57], v[56:57], v[0:1] op_sel_hi:[1,0]
	v_pk_mul_f32 v[54:55], v[54:55], v[0:1] op_sel_hi:[1,0]
	v_pk_mul_f32 v[52:53], v[52:53], v[0:1] op_sel_hi:[1,0]
	v_pk_mul_f32 v[50:51], v[50:51], v[0:1] op_sel_hi:[1,0]
	v_add_u32_e32 v176, 0x9000, v165
	v_pk_mul_f32 v[48:49], v[48:49], v[0:1] op_sel_hi:[1,0]
	s_waitcnt lgkmcnt(1)
	v_mfma_f32_32x32x16_bf16 v[50:65], v[74:77], v[70:73], v[50:65]
	ds_read2_b64 v[74:77], v176 offset0:32 offset1:34
	v_mul_f32_e64 v46, v46, v0
	v_mul_f32_e64 v47, v47, v0
	v_mul_f32_e64 v44, v44, v0
	v_mul_f32_e64 v45, v45, v0
	v_pk_mul_f32 v[42:43], v[42:43], v[0:1] op_sel_hi:[1,0]
	v_pk_mul_f32 v[40:41], v[40:41], v[0:1] op_sel_hi:[1,0]
	v_pk_mul_f32 v[38:39], v[38:39], v[0:1] op_sel_hi:[1,0]
	v_pk_mul_f32 v[36:37], v[36:37], v[0:1] op_sel_hi:[1,0]
	v_pk_mul_f32 v[34:35], v[34:35], v[0:1] op_sel_hi:[1,0]
	v_add_u32_e32 v177, 0x9800, v165
	v_pk_mul_f32 v[32:33], v[32:33], v[0:1] op_sel_hi:[1,0]
	s_waitcnt lgkmcnt(0)
	v_mfma_f32_32x32x16_bf16 v[34:49], v[74:77], v[70:73], v[34:49]
	ds_read2_b64 v[74:77], v176 offset0:36 offset1:38
	v_mul_f32_e64 v30, v30, v0
	v_mul_f32_e64 v31, v31, v0
	v_mul_f32_e64 v28, v28, v0
	v_mul_f32_e64 v29, v29, v0
	v_pk_mul_f32 v[26:27], v[26:27], v[0:1] op_sel_hi:[1,0]
	v_pk_mul_f32 v[24:25], v[24:25], v[0:1] op_sel_hi:[1,0]
	v_pk_mul_f32 v[22:23], v[22:23], v[0:1] op_sel_hi:[1,0]
	v_pk_mul_f32 v[20:21], v[20:21], v[0:1] op_sel_hi:[1,0]
	s_waitcnt lgkmcnt(0)
	v_mfma_f32_32x32x16_bf16 v[34:49], v[74:77], v[66:69], v[34:49]
	ds_read2_b64 v[74:77], v177 offset0:64 offset1:66
	v_mul_f32_e64 v18, v18, v0
	v_mul_f32_e64 v19, v19, v0
	v_add_u32_e32 v178, 0xa000, v165
	v_mul_f32_e64 v16, v16, v0
	v_mul_f32_e64 v17, v17, v0
	v_pk_mul_f32 v[14:15], v[14:15], v[0:1] op_sel_hi:[1,0]
	v_pk_mul_f32 v[12:13], v[12:13], v[0:1] op_sel_hi:[1,0]
	v_pk_mul_f32 v[10:11], v[10:11], v[0:1] op_sel_hi:[1,0]
	s_waitcnt lgkmcnt(0)
	v_mfma_f32_32x32x16_bf16 v[18:33], v[74:77], v[70:73], v[18:33]
	ds_read2_b64 v[74:77], v177 offset0:68 offset1:70
	v_mul_f32_e64 v8, v8, v0
	v_mul_f32_e64 v9, v9, v0
	v_mul_f32_e64 v6, v6, v0
	v_mul_f32_e64 v7, v7, v0
	v_pk_mul_f32 v[4:5], v[4:5], v[0:1] op_sel_hi:[1,0]
	v_pk_mul_f32 v[2:3], v[2:3], v[0:1] op_sel_hi:[1,0]
	v_fmac_f32_e32 v148, v175, v0
	s_waitcnt lgkmcnt(0)
	v_mfma_f32_32x32x16_bf16 v[18:33], v[74:77], v[66:69], v[18:33]
	ds_read2_b64 v[74:77], v178 offset0:96 offset1:98
	s_waitcnt lgkmcnt(0)
	v_mfma_f32_32x32x16_bf16 v[2:17], v[74:77], v[70:73], v[2:17]
	ds_read2_b64 v[70:73], v178 offset0:100 offset1:102
	s_waitcnt lgkmcnt(0)
	s_barrier
	v_mfma_f32_32x32x16_bf16 v[50:65], v[78:81], v[66:69], v[50:65]
	v_mfma_f32_32x32x16_bf16 v[2:17], v[70:73], v[66:69], v[2:17]
	s_cbranch_scc1 .LBB0_592
	s_waitcnt vmcnt(7)
	ds_write_b128 v160, v[118:121]
	s_waitcnt vmcnt(6)
	ds_write2_b64 v166, v[114:115], v[116:117] offset1:1
	s_waitcnt vmcnt(5)
	ds_write_b128 v160, v[126:129] offset:8704
	s_waitcnt vmcnt(4)
	ds_write2_b64 v167, v[122:123], v[124:125] offset1:1
	s_waitcnt vmcnt(3)
	ds_write_b128 v160, v[134:137] offset:17408
	s_waitcnt vmcnt(2)
	ds_write2_b64 v168, v[130:131], v[132:133] offset1:1
	s_waitcnt vmcnt(1)
	ds_write_b128 v160, v[142:145] offset:26112
	s_waitcnt vmcnt(0)
	ds_write2_b64 v169, v[138:139], v[140:141] offset1:1
	s_waitcnt lgkmcnt(0)
	s_barrier
	ds_read_b128 v[66:69], v159
	ds_read_b128 v[114:117], v159 offset:32
	s_waitcnt lgkmcnt(1)
	v_mfma_f32_32x32x16_bf16 v[66:81], v[66:69], v[110:113], 0
	v_readlane_b32 s1, v253, 17
	s_mov_b32 s4, 0xf149f2ca
	s_waitcnt lgkmcnt(0)
	v_mfma_f32_32x32x16_bf16 v[66:81], v[114:117], v[106:109], v[66:81]
	ds_read_b128 v[106:109], v159 offset:64
	ds_read_b128 v[110:113], v159 offset:96
	s_waitcnt lgkmcnt(1)
	v_mfma_f32_32x32x16_bf16 v[66:81], v[106:109], v[102:105], v[66:81]
	s_waitcnt lgkmcnt(0)
	v_mfma_f32_32x32x16_bf16 v[66:81], v[110:113], v[98:101], v[66:81]
	ds_read_b128 v[98:101], v159 offset:128
	ds_read_b128 v[102:105], v159 offset:160
	s_waitcnt lgkmcnt(1)
	v_mfma_f32_32x32x16_bf16 v[66:81], v[98:101], v[94:97], v[66:81]
	v_ashrrev_i32_e32 v100, 6, v157
	s_waitcnt lgkmcnt(0)
	v_mfma_f32_32x32x16_bf16 v[66:81], v[102:105], v[90:93], v[66:81]
	ds_read_b128 v[90:93], v159 offset:192
	ds_read_b128 v[94:97], v159 offset:224
	s_waitcnt lgkmcnt(1)
	v_mfma_f32_32x32x16_bf16 v[66:81], v[90:93], v[86:89], v[66:81]
	ds_read2_b64 v[86:89], v179 offset1:2
	s_waitcnt lgkmcnt(1)
	v_mfma_f32_32x32x16_bf16 v[66:81], v[94:97], v[82:85], v[66:81]
	ds_read2_b64 v[90:93], v179 offset0:4 offset1:6
	ds_read2_b64 v[94:97], v176 offset0:32 offset1:34
	s_nop 9
	v_max_f32_e32 v0, v67, v67
	v_max_f32_e32 v82, v66, v66
	v_max_f32_e32 v0, v82, v0
	v_max3_f32 v0, v0, v68, v69
	v_max3_f32 v0, v0, v70, v71
	v_max3_f32 v0, v0, v72, v73
	v_max3_f32 v0, v0, v74, v75
	v_max3_f32 v0, v0, v76, v77
	v_max3_f32 v0, v0, v78, v79
	v_max3_f32 v0, v0, v80, v81
	v_mov_b32_e32 v83, v0
	v_mov_b32_e32 v84, v81
	v_and_b32_e32 v82, 1, v100
	v_permlane32_swap_b32 v83, v0
	s_waitcnt lgkmcnt(0)
	v_max3_f32 v85, v149, v0, v83
	v_sub_f32_e32 v0, v149, v85
	v_pk_mul_f32 v[98:99], v[84:85], s[28:29] op_sel_hi:[1,0]
	v_mul_f32_e32 v0, 0x3e0293ee, v0
	v_fma_f32 v66, v66, s28, -v99
	v_fma_f32 v67, v67, s28, -v99
	v_fma_f32 v68, v68, s28, -v99
	v_fma_f32 v69, v69, s28, -v99
	v_fma_f32 v70, v70, s28, -v99
	v_fma_f32 v71, v71, s28, -v99
	v_fma_f32 v72, v72, s28, -v99
	v_fma_f32 v73, v73, s28, -v99
	v_fma_f32 v74, v74, s28, -v99
	v_fma_f32 v75, v75, s28, -v99
	v_fma_f32 v76, v76, s28, -v99
	v_fma_f32 v77, v77, s28, -v99
	v_fma_f32 v78, v78, s28, -v99
	v_fma_f32 v79, v79, s28, -v99
	v_fma_f32 v80, v80, s28, -v99
	v_sub_f32_e32 v81, v98, v99
	v_exp_f32_e32 v0, v0
	v_exp_f32_e32 v83, v66
	v_exp_f32_e32 v84, v67
	v_exp_f32_e32 v98, v68
	v_exp_f32_e32 v99, v69
	v_exp_f32_e32 v101, v70
	v_exp_f32_e32 v102, v71
	v_exp_f32_e32 v103, v72
	v_exp_f32_e32 v104, v73
	v_exp_f32_e32 v105, v74
	v_exp_f32_e32 v106, v75
	v_exp_f32_e32 v107, v76
	v_exp_f32_e32 v108, v77
	v_pk_mul_f32 v[48:49], v[48:49], v[0:1] op_sel_hi:[1,0]
	v_pk_mul_f32 v[46:47], v[46:47], v[0:1] op_sel_hi:[1,0]
	v_cvt_pk_bf16_f32 v66, v83, v84
	v_cvt_pk_bf16_f32 v67, v98, v99
	v_cvt_pk_bf16_f32 v68, v101, v102
	v_cvt_pk_bf16_f32 v69, v103, v104
	v_pk_mul_f32 v[44:45], v[44:45], v[0:1] op_sel_hi:[1,0]
	v_pk_mul_f32 v[42:43], v[42:43], v[0:1] op_sel_hi:[1,0]
	v_pk_mul_f32 v[40:41], v[40:41], v[0:1] op_sel_hi:[1,0]
	v_pk_mul_f32 v[38:39], v[38:39], v[0:1] op_sel_hi:[1,0]
	v_pk_mul_f32 v[36:37], v[36:37], v[0:1] op_sel_hi:[1,0]
	v_pk_mul_f32 v[34:35], v[34:35], v[0:1] op_sel_hi:[1,0]
	ds_read2_b64 v[74:77], v176 offset0:36 offset1:38
	v_exp_f32_e32 v109, v78
	v_exp_f32_e32 v110, v79
	v_exp_f32_e32 v111, v80
	v_exp_f32_e32 v112, v81
	v_mfma_f32_32x32x16_bf16 v[34:49], v[94:97], v[66:69], v[34:49]
	ds_read2_b64 v[78:81], v177 offset0:64 offset1:66
	v_cvt_pk_bf16_f32 v70, v105, v106
	v_cvt_pk_bf16_f32 v71, v107, v108
	v_cvt_pk_bf16_f32 v72, v109, v110
	v_cvt_pk_bf16_f32 v73, v111, v112
	v_pk_mul_f32 v[32:33], v[32:33], v[0:1] op_sel_hi:[1,0]
	v_pk_mul_f32 v[30:31], v[30:31], v[0:1] op_sel_hi:[1,0]
	v_pk_mul_f32 v[28:29], v[28:29], v[0:1] op_sel_hi:[1,0]
	v_pk_mul_f32 v[26:27], v[26:27], v[0:1] op_sel_hi:[1,0]
	v_pk_mul_f32 v[24:25], v[24:25], v[0:1] op_sel_hi:[1,0]
	v_pk_mul_f32 v[22:23], v[22:23], v[0:1] op_sel_hi:[1,0]
	v_pk_mul_f32 v[20:21], v[20:21], v[0:1] op_sel_hi:[1,0]
	v_pk_mul_f32 v[18:19], v[18:19], v[0:1] op_sel_hi:[1,0]
	s_waitcnt lgkmcnt(1)
	v_mfma_f32_32x32x16_bf16 v[34:49], v[74:77], v[70:73], v[34:49]
	ds_read2_b64 v[74:77], v177 offset0:68 offset1:70
	v_mul_f32_e64 v64, v64, v0
	v_mul_f32_e64 v65, v65, v0
	v_mul_f32_e64 v62, v62, v0
	v_mul_f32_e64 v63, v63, v0
	v_pk_mul_f32 v[60:61], v[60:61], v[0:1] op_sel_hi:[1,0]
	v_pk_mul_f32 v[58:59], v[58:59], v[0:1] op_sel_hi:[1,0]
	v_pk_mul_f32 v[56:57], v[56:57], v[0:1] op_sel_hi:[1,0]
	v_pk_mul_f32 v[54:55], v[54:55], v[0:1] op_sel_hi:[1,0]
	s_waitcnt lgkmcnt(1)
	v_mfma_f32_32x32x16_bf16 v[18:33], v[78:81], v[66:69], v[18:33]
	v_add_f32_e32 v78, 0, v83
	v_add_f32_e32 v78, v84, v78
	v_add_f32_e32 v78, v98, v78
	v_add_f32_e32 v78, v99, v78
	v_add_f32_e32 v83, v101, v78
	ds_read2_b64 v[78:81], v178 offset0:96 offset1:98
	v_pk_mul_f32 v[52:53], v[52:53], v[0:1] op_sel_hi:[1,0]
	s_waitcnt lgkmcnt(1)
	v_mfma_f32_32x32x16_bf16 v[18:33], v[74:77], v[70:73], v[18:33]
	v_add_f32_e32 v74, v102, v83
	v_add_f32_e32 v74, v103, v74
	v_add_f32_e32 v74, v104, v74
	v_add_f32_e32 v74, v105, v74
	v_mul_f32_e64 v50, v50, v0
	v_mul_f32_e64 v51, v51, v0
	v_add_f32_e32 v74, v106, v74
	v_pk_mul_f32 v[16:17], v[16:17], v[0:1] op_sel_hi:[1,0]
	v_mfma_f32_32x32x16_bf16 v[50:65], v[86:89], v[66:69], v[50:65]
	v_mul_f32_e64 v14, v14, v0
	v_mul_f32_e64 v15, v15, v0
	v_mul_f32_e64 v12, v12, v0
	v_mul_f32_e64 v13, v13, v0
	v_mul_f32_e64 v10, v10, v0
	v_mul_f32_e64 v11, v11, v0
	v_pk_mul_f32 v[8:9], v[8:9], v[0:1] op_sel_hi:[1,0]
	v_pk_mul_f32 v[6:7], v[6:7], v[0:1] op_sel_hi:[1,0]
	v_pk_mul_f32 v[4:5], v[4:5], v[0:1] op_sel_hi:[1,0]
	v_pk_mul_f32 v[2:3], v[2:3], v[0:1] op_sel_hi:[1,0]
	v_add_f32_e32 v83, v107, v74
	ds_read2_b64 v[74:77], v178 offset0:100 offset1:102
	s_waitcnt lgkmcnt(1)
	v_mfma_f32_32x32x16_bf16 v[2:17], v[78:81], v[66:69], v[2:17]
	v_add_f32_e32 v66, v108, v83
	v_add_f32_e32 v66, v109, v66
	v_add_f32_e32 v66, v110, v66
	v_add_f32_e32 v66, v111, v66
	v_add_f32_e32 v66, v112, v66
	v_fmac_f32_e32 v66, v148, v0
	v_mov_b32_e32 v0, v66
	v_mfma_f32_32x32x16_bf16 v[50:65], v[90:93], v[70:73], v[50:65]
	v_lshlrev_b32_e32 v67, 2, v155
	s_nop 1
	v_permlane32_swap_b32 v0, v66
	s_waitcnt lgkmcnt(0)
	s_barrier
	v_add_f32_e32 v0, v66, v0
	v_lshlrev_b32_e32 v66, 9, v100
	v_add3_u32 v66, s1, v66, v67
	ds_write2st64_b32 v66, v85, v0 offset1:1
	v_lshlrev_b32_e32 v0, 14, v100
	v_add3_u32 v0, 0, v0, v67
	v_mfma_f32_32x32x16_bf16 v[2:17], v[74:77], v[70:73], v[2:17]
	s_nop 1
	ds_write2st64_b32 v0, v50, v51 offset1:1
	ds_write2st64_b32 v0, v52, v53 offset0:2 offset1:3
	ds_write2st64_b32 v0, v54, v55 offset0:4 offset1:5
	ds_write2st64_b32 v0, v56, v57 offset0:6 offset1:7
	ds_write2st64_b32 v0, v58, v59 offset0:8 offset1:9
	ds_write2st64_b32 v0, v60, v61 offset0:10 offset1:11
	ds_write2st64_b32 v0, v62, v63 offset0:12 offset1:13
	ds_write2st64_b32 v0, v64, v65 offset0:14 offset1:15
	ds_write2st64_b32 v0, v34, v35 offset0:16 offset1:17
	ds_write2st64_b32 v0, v36, v37 offset0:18 offset1:19
	ds_write2st64_b32 v0, v38, v39 offset0:20 offset1:21
	ds_write2st64_b32 v0, v40, v41 offset0:22 offset1:23
	ds_write2st64_b32 v0, v42, v43 offset0:24 offset1:25
	ds_write2st64_b32 v0, v44, v45 offset0:26 offset1:27
	ds_write2st64_b32 v0, v46, v47 offset0:28 offset1:29
	ds_write2st64_b32 v0, v48, v49 offset0:30 offset1:31
	ds_write2st64_b32 v0, v18, v19 offset0:32 offset1:33
	ds_write2st64_b32 v0, v20, v21 offset0:34 offset1:35
	ds_write2st64_b32 v0, v22, v23 offset0:36 offset1:37
	ds_write2st64_b32 v0, v24, v25 offset0:38 offset1:39
	ds_write2st64_b32 v0, v26, v27 offset0:40 offset1:41
	ds_write2st64_b32 v0, v28, v29 offset0:42 offset1:43
	ds_write2st64_b32 v0, v30, v31 offset0:44 offset1:45
	ds_write2st64_b32 v0, v32, v33 offset0:46 offset1:47
	ds_write2st64_b32 v0, v2, v3 offset0:48 offset1:49
	ds_write2st64_b32 v0, v4, v5 offset0:50 offset1:51
	ds_write2st64_b32 v0, v6, v7 offset0:52 offset1:53
	ds_write2st64_b32 v0, v8, v9 offset0:54 offset1:55
	ds_write2st64_b32 v0, v10, v11 offset0:56 offset1:57
	ds_write2st64_b32 v0, v12, v13 offset0:58 offset1:59
	ds_write2st64_b32 v0, v14, v15 offset0:60 offset1:61
	ds_write2st64_b32 v0, v16, v17 offset0:62 offset1:63
	v_lshlrev_b32_e32 v0, 9, v82
	v_add3_u32 v0, s1, v0, v67
	s_waitcnt lgkmcnt(0)
	s_barrier
	ds_read2st64_b32 v[4:5], v0 offset1:1
	ds_read2st64_b32 v[6:7], v0 offset0:4 offset1:5
	ds_read2st64_b32 v[8:9], v0 offset0:8 offset1:9
	ds_read2st64_b32 v[10:11], v0 offset0:12 offset1:13
	s_mov_b32 s1, s31
	s_lshl_b64 s[0:1], s[0:1], 11
	s_waitcnt lgkmcnt(2)
	v_max3_f32 v0, v4, s4, v6
	s_add_u32 s4, s80, s0
	s_waitcnt lgkmcnt(0)
	v_max3_f32 v0, v0, v8, v10
	v_sub_f32_e32 v2, v4, v0
	v_mul_f32_e32 v2, 0x3e0293ee, v2
	v_exp_f32_e32 v3, v2
	v_sub_f32_e32 v2, v6, v0
	v_mul_f32_e32 v2, 0x3e0293ee, v2
	v_exp_f32_e32 v2, v2
	v_mov_b32_e32 v4, v7
	s_addc_u32 s5, s81, s1
	v_pk_mul_f32 v[6:7], v[4:5], v[2:3]
	v_sub_f32_e32 v4, v8, v0
	v_sub_f32_e32 v0, v10, v0
	v_mul_f32_e32 v4, 0x3e0293ee, v4
	v_mul_f32_e32 v0, 0x3e0293ee, v0
	v_exp_f32_e32 v5, v4
	v_exp_f32_e32 v4, v0
	v_add_f32_e32 v0, 0, v7
	v_mov_b32_e32 v8, v11
	v_add_f32_e32 v0, v6, v0
	v_pk_mul_f32 v[6:7], v[8:9], v[4:5]
	s_nop 0
	v_add_f32_e32 v0, v7, v0
	v_add_f32_e32 v0, v6, v0
	v_div_scale_f32 v6, s[0:1], v0, v0, 1.0
	v_rcp_f32_e32 v7, v6
	s_lshl_b32 s0, s6, 1
	s_add_u32 s0, s4, s0
	s_addc_u32 s1, s5, 0
	v_fma_f32 v8, -v6, v7, 1.0
	v_fmac_f32_e32 v7, v8, v7
	v_div_scale_f32 v8, vcc, 1.0, v0, 1.0
	v_mul_f32_e32 v9, v8, v7
	v_fma_f32 v10, -v6, v9, v8
	v_fmac_f32_e32 v9, v10, v7
	v_fma_f32 v6, -v6, v9, v8
	v_div_fmas_f32 v6, v6, v7, v9
	v_div_fixup_f32 v0, v6, v0, 1.0
	v_lshl_add_u32 v6, v82, 14, 0
	v_lshlrev_b32_e32 v7, 12, v154
	v_add3_u32 v7, v6, v7, v67
	ds_read2st64_b32 v[8:9], v7 offset1:1
	ds_read2st64_b32 v[10:11], v7 offset0:128 offset1:129
	v_mov_b32_e32 v6, v3
	v_add_u32_e32 v24, 0x10000, v7
	v_add_u32_e32 v25, 0x18000, v7
	v_add_u32_e32 v27, 0x10100, v7
	v_add_u32_e32 v28, 0x18100, v7
	ds_read2st64_b32 v[12:13], v7 offset0:2 offset1:3
	ds_read2st64_b32 v[14:15], v7 offset0:4 offset1:5
	ds_read2st64_b32 v[16:17], v7 offset0:6 offset1:7
	s_waitcnt lgkmcnt(4)
	v_pk_fma_f32 v[8:9], v[8:9], v[6:7], 0 op_sel_hi:[1,0,0]
	v_add_u32_e32 v31, 0x18300, v7
	ds_read2st64_b32 v[18:19], v7 offset0:130 offset1:131
	ds_read2st64_b32 v[20:21], v7 offset0:132 offset1:133
	ds_read2st64_b32 v[22:23], v7 offset0:134 offset1:135
	s_waitcnt lgkmcnt(6)
	v_pk_fma_f32 v[8:9], v[10:11], v[2:3], v[8:9] op_sel_hi:[1,0,1]
	v_mov_b32_e32 v10, v5
	v_add_u32_e32 v3, 0x10200, v7
	v_add_u32_e32 v5, 0x18200, v7
	v_add_u32_e32 v11, 0x10300, v7
	ds_read_b32 v24, v24
	ds_read_b32 v26, v25
	ds_read_b32 v25, v27
	ds_read_b32 v27, v28
	ds_read_b32 v28, v3
	ds_read_b32 v30, v5
	ds_read_b32 v29, v11
	ds_read_b32 v31, v31
	s_waitcnt lgkmcnt(13)
	v_pk_fma_f32 v[12:13], v[6:7], v[12:13], 0 op_sel_hi:[0,1,0]
	s_waitcnt lgkmcnt(5)
	v_pk_fma_f32 v[8:9], v[10:11], v[24:25], v[8:9] op_sel_hi:[0,1,1]
	v_pk_fma_f32 v[12:13], v[2:3], v[18:19], v[12:13] op_sel_hi:[0,1,1]
	v_add_u32_e32 v3, 0x10400, v7
	v_pk_fma_f32 v[14:15], v[6:7], v[14:15], 0 op_sel_hi:[0,1,0]
	s_waitcnt lgkmcnt(4)
	v_pk_fma_f32 v[8:9], v[4:5], v[26:27], v[8:9] op_sel_hi:[0,1,1]
	s_waitcnt lgkmcnt(1)
	v_pk_fma_f32 v[12:13], v[10:11], v[28:29], v[12:13] op_sel_hi:[0,1,1]
	v_add_u32_e32 v11, 0x10500, v7
	v_add_u32_e32 v24, 0x18500, v7
	v_pk_fma_f32 v[14:15], v[2:3], v[20:21], v[14:15] op_sel_hi:[0,1,1]
	v_add_u32_e32 v25, 0x10600, v7
	v_add_u32_e32 v26, 0x18600, v7
	v_add_u32_e32 v27, 0x10700, v7
	s_waitcnt lgkmcnt(0)
	v_pk_fma_f32 v[12:13], v[4:5], v[30:31], v[12:13] op_sel_hi:[0,1,1]
	v_add_u32_e32 v5, 0x18400, v7
	v_add_u32_e32 v28, 0x18700, v7
	ds_read_b32 v18, v3
	ds_read_b32 v20, v5
	ds_read_b32 v19, v11
	ds_read_b32 v21, v24
	ds_read_b32 v24, v25
	ds_read_b32 v26, v26
	ds_read_b32 v25, v27
	ds_read_b32 v27, v28
	s_waitcnt lgkmcnt(5)
	v_pk_fma_f32 v[14:15], v[10:11], v[18:19], v[14:15] op_sel_hi:[0,1,1]
	s_waitcnt lgkmcnt(4)
	v_pk_fma_f32 v[14:15], v[4:5], v[20:21], v[14:15] op_sel_hi:[0,1,1]
	ds_read2st64_b32 v[18:19], v7 offset0:8 offset1:9
	ds_read2st64_b32 v[20:21], v7 offset0:136 offset1:137
	v_pk_fma_f32 v[16:17], v[6:7], v[16:17], 0 op_sel_hi:[0,1,0]
	v_pk_fma_f32 v[16:17], v[2:3], v[22:23], v[16:17] op_sel_hi:[0,1,1]
	s_waitcnt lgkmcnt(3)
	v_pk_fma_f32 v[16:17], v[10:11], v[24:25], v[16:17] op_sel_hi:[0,1,1]
	s_waitcnt lgkmcnt(2)
	v_pk_fma_f32 v[16:17], v[4:5], v[26:27], v[16:17] op_sel_hi:[0,1,1]
	v_add_u32_e32 v3, 0x10800, v7
	v_add_u32_e32 v35, 0x18900, v7
	ds_read2st64_b32 v[22:23], v7 offset0:10 offset1:11
	ds_read2st64_b32 v[24:25], v7 offset0:12 offset1:13
	ds_read2st64_b32 v[26:27], v7 offset0:14 offset1:15
	s_waitcnt lgkmcnt(4)
	v_pk_fma_f32 v[18:19], v[6:7], v[18:19], 0 op_sel_hi:[0,1,0]
	v_add_u32_e32 v36, 0x10a00, v7
	v_add_u32_e32 v37, 0x18a00, v7
	v_add_u32_e32 v39, 0x10b00, v7
	v_add_u32_e32 v5, 0x18800, v7
	v_add_u32_e32 v11, 0x10900, v7
	ds_read2st64_b32 v[28:29], v7 offset0:138 offset1:139
	ds_read2st64_b32 v[30:31], v7 offset0:140 offset1:141
	ds_read2st64_b32 v[32:33], v7 offset0:142 offset1:143
	s_waitcnt lgkmcnt(6)
	v_pk_fma_f32 v[18:19], v[2:3], v[20:21], v[18:19] op_sel_hi:[0,1,1]
	v_add_u32_e32 v40, 0x18b00, v7
	ds_read_b32 v20, v3
	ds_read_b32 v34, v5
	ds_read_b32 v21, v11
	ds_read_b32 v35, v35
	ds_read_b32 v36, v36
	ds_read_b32 v38, v37
	ds_read_b32 v37, v39
	ds_read_b32 v39, v40
	s_waitcnt lgkmcnt(5)
	v_pk_fma_f32 v[18:19], v[10:11], v[20:21], v[18:19] op_sel_hi:[0,1,1]
	v_pk_fma_f32 v[20:21], v[6:7], v[22:23], 0 op_sel_hi:[0,1,0]
	v_pk_fma_f32 v[20:21], v[2:3], v[28:29], v[20:21] op_sel_hi:[0,1,1]
	v_add_u32_e32 v3, 0x10c00, v7
	v_pk_fma_f32 v[22:23], v[6:7], v[24:25], 0 op_sel_hi:[0,1,0]
	s_waitcnt lgkmcnt(4)
	v_pk_fma_f32 v[18:19], v[4:5], v[34:35], v[18:19] op_sel_hi:[0,1,1]
	s_waitcnt lgkmcnt(1)
	v_pk_fma_f32 v[20:21], v[10:11], v[36:37], v[20:21] op_sel_hi:[0,1,1]
	v_add_u32_e32 v29, 0x18d00, v7
	v_pk_fma_f32 v[22:23], v[2:3], v[30:31], v[22:23] op_sel_hi:[0,1,1]
	v_add_u32_e32 v30, 0x10e00, v7
	v_add_u32_e32 v31, 0x18e00, v7
	v_add_u32_e32 v35, 0x10f00, v7
	s_waitcnt lgkmcnt(0)
	v_pk_fma_f32 v[20:21], v[4:5], v[38:39], v[20:21] op_sel_hi:[0,1,1]
	v_add_u32_e32 v5, 0x18c00, v7
	v_add_u32_e32 v11, 0x10d00, v7
	v_add_u32_e32 v7, 0x18f00, v7
	ds_read_b32 v24, v3
	ds_read_b32 v28, v5
	ds_read_b32 v25, v11
	ds_read_b32 v29, v29
	ds_read_b32 v30, v30
	ds_read_b32 v34, v31
	ds_read_b32 v31, v35
	ds_read_b32 v35, v7
	v_pk_fma_f32 v[6:7], v[6:7], v[26:27], 0 op_sel_hi:[0,1,0]
	v_pk_fma_f32 v[2:3], v[2:3], v[32:33], v[6:7] op_sel_hi:[0,1,1]
	s_waitcnt lgkmcnt(5)
	v_pk_fma_f32 v[22:23], v[10:11], v[24:25], v[22:23] op_sel_hi:[0,1,1]
	s_waitcnt lgkmcnt(1)
	v_pk_fma_f32 v[2:3], v[10:11], v[30:31], v[2:3] op_sel_hi:[0,1,1]
	v_pk_fma_f32 v[22:23], v[4:5], v[28:29], v[22:23] op_sel_hi:[0,1,1]
	s_waitcnt lgkmcnt(0)
	v_pk_fma_f32 v[2:3], v[4:5], v[34:35], v[2:3] op_sel_hi:[0,1,1]
	v_pk_mul_f32 v[8:9], v[8:9], v[0:1] op_sel_hi:[1,0]
	v_pk_mul_f32 v[12:13], v[0:1], v[12:13] op_sel_hi:[0,1]
	v_pk_mul_f32 v[14:15], v[0:1], v[14:15] op_sel_hi:[0,1]
	v_pk_mul_f32 v[16:17], v[0:1], v[16:17] op_sel_hi:[0,1]
	v_pk_mul_f32 v[18:19], v[0:1], v[18:19] op_sel_hi:[0,1]
	v_pk_mul_f32 v[20:21], v[0:1], v[20:21] op_sel_hi:[0,1]
	v_pk_mul_f32 v[22:23], v[0:1], v[22:23] op_sel_hi:[0,1]
	v_pk_mul_f32 v[2:3], v[0:1], v[2:3] op_sel_hi:[0,1]
	v_lshlrev_b32_e32 v0, 11, v147
	v_lshl_or_b32 v0, v82, 16, v0
	v_lshlrev_b32_e32 v6, 5, v154
	v_lshl_add_u64 v[4:5], s[0:1], 0, v[0:1]
	v_ashrrev_i32_e32 v7, 31, v6
	v_lshl_add_u64 v[4:5], v[6:7], 1, v[4:5]
	v_mov_b32_e32 v147, v1
	v_lshl_add_u64 v[4:5], v[4:5], 0, v[146:147]
	s_mov_b64 s[0:1], 0x4328400
	v_lshl_add_u64 v[6:7], v[4:5], 0, s[0:1]
	s_mov_b32 s0, 0x4328000
	v_add_co_u32_e32 v4, vcc, s0, v4
	v_cvt_pk_bf16_f32 v8, v8, v9
	v_cvt_pk_bf16_f32 v9, v12, v13
	v_addc_co_u32_e32 v5, vcc, 0, v5, vcc
	global_store_dwordx2 v[4:5], v[8:9], off offset:1024
	v_cvt_pk_bf16_f32 v4, v14, v15
	v_cvt_pk_bf16_f32 v5, v16, v17
	global_store_dwordx2 v[6:7], v[4:5], off offset:16
	v_cvt_pk_bf16_f32 v4, v18, v19
	v_cvt_pk_bf16_f32 v5, v20, v21
	global_store_dwordx2 v[6:7], v[4:5], off offset:32
	v_cvt_pk_bf16_f32 v4, v22, v23
	v_cvt_pk_bf16_f32 v5, v2, v3
	global_store_dwordx2 v[6:7], v[4:5], off offset:48
	s_barrier
	s_mov_b64 s[0:1], 0
